# speedup vs baseline: 1.0142x; 1.0142x over previous
.LBB0_53:
	s_waitcnt lgkmcnt(0)
	v_lshl_add_u32 v3, s18, 15, v220
	ds_read_b64_tr_b16 v[150:151], v3 offset:0
	ds_read_b64_tr_b16 v[152:153], v3 offset:0x800
	ds_read_b64_tr_b16 v[154:155], v3 offset:0x1000
	ds_read_b64_tr_b16 v[156:157], v3 offset:0x1800
	ds_read_b64_tr_b16 v[158:159], v3 offset:0x2000
	ds_read_b64_tr_b16 v[160:161], v3 offset:0x2800
	ds_read_b64_tr_b16 v[162:163], v3 offset:0x3000
	ds_read_b64_tr_b16 v[164:165], v3 offset:0x3800
	s_waitcnt lgkmcnt(6)
	s_nop 0
	v_mfma_f32_32x32x16_bf16 v[130:145], v[146:149], v[150:153], v[130:145]
	ds_read_b64_tr_b16 v[150:151], v3 offset:0x200
	ds_read_b64_tr_b16 v[152:153], v3 offset:0xa00
	s_waitcnt lgkmcnt(6)
	v_mfma_f32_32x32x16_bf16 v[130:145], v[12:15], v[154:157], v[130:145]
	ds_read_b64_tr_b16 v[154:155], v3 offset:0x1200
	ds_read_b64_tr_b16 v[156:157], v3 offset:0x1a00
	s_waitcnt lgkmcnt(6)
	v_mfma_f32_32x32x16_bf16 v[130:145], v[8:11], v[158:161], v[130:145]
	ds_read_b64_tr_b16 v[158:159], v3 offset:0x2200
	ds_read_b64_tr_b16 v[160:161], v3 offset:0x2a00
	s_waitcnt lgkmcnt(6)
	v_mfma_f32_32x32x16_bf16 v[130:145], v[4:7], v[162:165], v[130:145]
	ds_read_b64_tr_b16 v[162:163], v3 offset:0x3200
	ds_read_b64_tr_b16 v[164:165], v3 offset:0x3a00
	s_waitcnt lgkmcnt(6)
	v_mfma_f32_32x32x16_bf16 v[114:129], v[146:149], v[150:153], v[114:129]
	ds_read_b64_tr_b16 v[150:151], v3 offset:0x400
	ds_read_b64_tr_b16 v[152:153], v3 offset:0xc00
	s_waitcnt lgkmcnt(6)
	v_mfma_f32_32x32x16_bf16 v[114:129], v[12:15], v[154:157], v[114:129]
	ds_read_b64_tr_b16 v[154:155], v3 offset:0x1400
	ds_read_b64_tr_b16 v[156:157], v3 offset:0x1c00
	s_waitcnt lgkmcnt(6)
	v_mfma_f32_32x32x16_bf16 v[114:129], v[8:11], v[158:161], v[114:129]
	ds_read_b64_tr_b16 v[158:159], v3 offset:0x2400
	ds_read_b64_tr_b16 v[160:161], v3 offset:0x2c00
	s_waitcnt lgkmcnt(6)
	v_mfma_f32_32x32x16_bf16 v[114:129], v[4:7], v[162:165], v[114:129]
	ds_read_b64_tr_b16 v[162:163], v3 offset:0x3400
	ds_read_b64_tr_b16 v[164:165], v3 offset:0x3c00
	s_waitcnt lgkmcnt(6)
	v_mfma_f32_32x32x16_bf16 v[98:113], v[146:149], v[150:153], v[98:113]
	ds_read_b64_tr_b16 v[150:151], v3 offset:0x600
	ds_read_b64_tr_b16 v[152:153], v3 offset:0xe00
	s_waitcnt lgkmcnt(6)
	v_mfma_f32_32x32x16_bf16 v[98:113], v[12:15], v[154:157], v[98:113]
	ds_read_b64_tr_b16 v[154:155], v3 offset:0x1600
	ds_read_b64_tr_b16 v[156:157], v3 offset:0x1e00
	s_waitcnt lgkmcnt(6)
	v_mfma_f32_32x32x16_bf16 v[98:113], v[8:11], v[158:161], v[98:113]
	ds_read_b64_tr_b16 v[158:159], v3 offset:0x2600
	ds_read_b64_tr_b16 v[160:161], v3 offset:0x2e00
	s_waitcnt lgkmcnt(6)
	v_mfma_f32_32x32x16_bf16 v[98:113], v[4:7], v[162:165], v[98:113]
	ds_read_b64_tr_b16 v[162:163], v3 offset:0x3600
	ds_read_b64_tr_b16 v[164:165], v3 offset:0x3e00
	s_waitcnt lgkmcnt(6)
	v_mfma_f32_32x32x16_bf16 v[82:97], v[146:149], v[150:153], v[82:97]
	ds_read_b64_tr_b16 v[150:151], v3 offset:0x4000
	ds_read_b64_tr_b16 v[152:153], v3 offset:0x4800
	s_waitcnt lgkmcnt(6)
	v_mfma_f32_32x32x16_bf16 v[82:97], v[12:15], v[154:157], v[82:97]
	ds_read_b64_tr_b16 v[154:155], v3 offset:0x5000
	ds_read_b64_tr_b16 v[156:157], v3 offset:0x5800
	s_waitcnt lgkmcnt(6)
	v_mfma_f32_32x32x16_bf16 v[82:97], v[8:11], v[158:161], v[82:97]
	ds_read_b64_tr_b16 v[158:159], v3 offset:0x6000
	ds_read_b64_tr_b16 v[160:161], v3 offset:0x6800
	s_waitcnt lgkmcnt(6)
	v_mfma_f32_32x32x16_bf16 v[82:97], v[4:7], v[162:165], v[82:97]
	ds_read_b64_tr_b16 v[162:163], v3 offset:0x7000
	ds_read_b64_tr_b16 v[164:165], v3 offset:0x7800
	s_waitcnt lgkmcnt(6)
	v_mfma_f32_32x32x16_bf16 v[66:81], v[146:149], v[150:153], v[66:81]
	ds_read_b64_tr_b16 v[150:151], v3 offset:0x4200
	ds_read_b64_tr_b16 v[152:153], v3 offset:0x4a00
	s_waitcnt lgkmcnt(6)
	v_mfma_f32_32x32x16_bf16 v[66:81], v[12:15], v[154:157], v[66:81]
	ds_read_b64_tr_b16 v[154:155], v3 offset:0x5200
	ds_read_b64_tr_b16 v[156:157], v3 offset:0x5a00
	s_waitcnt lgkmcnt(6)
	v_mfma_f32_32x32x16_bf16 v[66:81], v[8:11], v[158:161], v[66:81]
	ds_read_b64_tr_b16 v[158:159], v3 offset:0x6200
	ds_read_b64_tr_b16 v[160:161], v3 offset:0x6a00
	s_waitcnt lgkmcnt(6)
	v_mfma_f32_32x32x16_bf16 v[66:81], v[4:7], v[162:165], v[66:81]
	ds_read_b64_tr_b16 v[162:163], v3 offset:0x7200
	ds_read_b64_tr_b16 v[164:165], v3 offset:0x7a00
	s_waitcnt lgkmcnt(6)
	v_mfma_f32_32x32x16_bf16 v[50:65], v[146:149], v[150:153], v[50:65]
	ds_read_b64_tr_b16 v[150:151], v3 offset:0x4400
	ds_read_b64_tr_b16 v[152:153], v3 offset:0x4c00
	s_waitcnt lgkmcnt(6)
	v_mfma_f32_32x32x16_bf16 v[50:65], v[12:15], v[154:157], v[50:65]
	ds_read_b64_tr_b16 v[154:155], v3 offset:0x5400
	ds_read_b64_tr_b16 v[156:157], v3 offset:0x5c00
	s_waitcnt lgkmcnt(6)
	v_mfma_f32_32x32x16_bf16 v[50:65], v[8:11], v[158:161], v[50:65]
	ds_read_b64_tr_b16 v[158:159], v3 offset:0x6400
	ds_read_b64_tr_b16 v[160:161], v3 offset:0x6c00
	s_waitcnt lgkmcnt(6)
	v_mfma_f32_32x32x16_bf16 v[50:65], v[4:7], v[162:165], v[50:65]
	ds_read_b64_tr_b16 v[162:163], v3 offset:0x7400
	ds_read_b64_tr_b16 v[164:165], v3 offset:0x7c00
	s_waitcnt lgkmcnt(6)
	v_mfma_f32_32x32x16_bf16 v[34:49], v[146:149], v[150:153], v[34:49]
	ds_read_b64_tr_b16 v[150:151], v3 offset:0x4600
	ds_read_b64_tr_b16 v[152:153], v3 offset:0x4e00
	s_waitcnt lgkmcnt(6)
	v_mfma_f32_32x32x16_bf16 v[34:49], v[12:15], v[154:157], v[34:49]
	ds_read_b64_tr_b16 v[154:155], v3 offset:0x5600
	ds_read_b64_tr_b16 v[156:157], v3 offset:0x5e00
	s_waitcnt lgkmcnt(6)
	v_mfma_f32_32x32x16_bf16 v[34:49], v[8:11], v[158:161], v[34:49]
	ds_read_b64_tr_b16 v[158:159], v3 offset:0x6600
	ds_read_b64_tr_b16 v[160:161], v3 offset:0x6e00
	s_waitcnt lgkmcnt(6)
	v_mfma_f32_32x32x16_bf16 v[34:49], v[4:7], v[162:165], v[34:49]
	ds_read_b64_tr_b16 v[162:163], v3 offset:0x7600
	ds_read_b64_tr_b16 v[164:165], v3 offset:0x7e00
	s_waitcnt lgkmcnt(6)
	v_mfma_f32_32x32x16_bf16 v[18:33], v[146:149], v[150:153], v[18:33]
	s_waitcnt lgkmcnt(4)
	v_mfma_f32_32x32x16_bf16 v[18:33], v[12:15], v[154:157], v[18:33]
	s_waitcnt lgkmcnt(2)
	v_mfma_f32_32x32x16_bf16 v[18:33], v[8:11], v[158:161], v[18:33]
	s_waitcnt lgkmcnt(0)
	v_mfma_f32_32x32x16_bf16 v[18:33], v[4:7], v[162:165], v[18:33]

.LBB0_63:
	s_waitcnt lgkmcnt(0)
	v_lshl_add_u32 v3, s0, 15, v220
	ds_read_b64_tr_b16 v[150:151], v3 offset:0
	ds_read_b64_tr_b16 v[152:153], v3 offset:0x800
	ds_read_b64_tr_b16 v[154:155], v3 offset:0x1000
	ds_read_b64_tr_b16 v[156:157], v3 offset:0x1800
	ds_read_b64_tr_b16 v[158:159], v3 offset:0x2000
	ds_read_b64_tr_b16 v[160:161], v3 offset:0x2800
	ds_read_b64_tr_b16 v[162:163], v3 offset:0x3000
	ds_read_b64_tr_b16 v[164:165], v3 offset:0x3800
	s_waitcnt lgkmcnt(6)
	v_mfma_f32_32x32x16_bf16 v[130:145], v[146:149], v[150:153], v[130:145]
	ds_read_b64_tr_b16 v[150:151], v3 offset:0x200
	ds_read_b64_tr_b16 v[152:153], v3 offset:0xa00
	s_waitcnt lgkmcnt(6)
	v_mfma_f32_32x32x16_bf16 v[130:145], v[12:15], v[154:157], v[130:145]
	ds_read_b64_tr_b16 v[154:155], v3 offset:0x1200
	ds_read_b64_tr_b16 v[156:157], v3 offset:0x1a00
	s_waitcnt lgkmcnt(6)
	v_mfma_f32_32x32x16_bf16 v[130:145], v[8:11], v[158:161], v[130:145]
	ds_read_b64_tr_b16 v[158:159], v3 offset:0x2200
	ds_read_b64_tr_b16 v[160:161], v3 offset:0x2a00
	s_waitcnt lgkmcnt(6)
	v_mfma_f32_32x32x16_bf16 v[130:145], v[4:7], v[162:165], v[130:145]
	ds_read_b64_tr_b16 v[162:163], v3 offset:0x3200
	ds_read_b64_tr_b16 v[164:165], v3 offset:0x3a00
	s_waitcnt lgkmcnt(6)
	v_mfma_f32_32x32x16_bf16 v[114:129], v[146:149], v[150:153], v[114:129]
	ds_read_b64_tr_b16 v[150:151], v3 offset:0x400
	ds_read_b64_tr_b16 v[152:153], v3 offset:0xc00
	s_waitcnt lgkmcnt(6)
	v_mfma_f32_32x32x16_bf16 v[114:129], v[12:15], v[154:157], v[114:129]
	ds_read_b64_tr_b16 v[154:155], v3 offset:0x1400
	ds_read_b64_tr_b16 v[156:157], v3 offset:0x1c00
	s_waitcnt lgkmcnt(6)
	v_mfma_f32_32x32x16_bf16 v[114:129], v[8:11], v[158:161], v[114:129]
	ds_read_b64_tr_b16 v[158:159], v3 offset:0x2400
	ds_read_b64_tr_b16 v[160:161], v3 offset:0x2c00
	s_waitcnt lgkmcnt(6)
	v_mfma_f32_32x32x16_bf16 v[114:129], v[4:7], v[162:165], v[114:129]
	ds_read_b64_tr_b16 v[162:163], v3 offset:0x3400
	ds_read_b64_tr_b16 v[164:165], v3 offset:0x3c00
	s_waitcnt lgkmcnt(6)
	v_mfma_f32_32x32x16_bf16 v[98:113], v[146:149], v[150:153], v[98:113]
	ds_read_b64_tr_b16 v[150:151], v3 offset:0x600
	ds_read_b64_tr_b16 v[152:153], v3 offset:0xe00
	s_waitcnt lgkmcnt(6)
	v_mfma_f32_32x32x16_bf16 v[98:113], v[12:15], v[154:157], v[98:113]
	ds_read_b64_tr_b16 v[154:155], v3 offset:0x1600
	ds_read_b64_tr_b16 v[156:157], v3 offset:0x1e00
	s_waitcnt lgkmcnt(6)
	v_mfma_f32_32x32x16_bf16 v[98:113], v[8:11], v[158:161], v[98:113]
	ds_read_b64_tr_b16 v[158:159], v3 offset:0x2600
	ds_read_b64_tr_b16 v[160:161], v3 offset:0x2e00
	s_waitcnt lgkmcnt(6)
	v_mfma_f32_32x32x16_bf16 v[98:113], v[4:7], v[162:165], v[98:113]
	ds_read_b64_tr_b16 v[162:163], v3 offset:0x3600
	ds_read_b64_tr_b16 v[164:165], v3 offset:0x3e00
	s_waitcnt lgkmcnt(6)
	v_mfma_f32_32x32x16_bf16 v[82:97], v[146:149], v[150:153], v[82:97]
	ds_read_b64_tr_b16 v[150:151], v3 offset:0x4000
	ds_read_b64_tr_b16 v[152:153], v3 offset:0x4800
	s_waitcnt lgkmcnt(6)
	v_mfma_f32_32x32x16_bf16 v[82:97], v[12:15], v[154:157], v[82:97]
	ds_read_b64_tr_b16 v[154:155], v3 offset:0x5000
	ds_read_b64_tr_b16 v[156:157], v3 offset:0x5800
	s_waitcnt lgkmcnt(6)
	v_mfma_f32_32x32x16_bf16 v[82:97], v[8:11], v[158:161], v[82:97]
	ds_read_b64_tr_b16 v[158:159], v3 offset:0x6000
	ds_read_b64_tr_b16 v[160:161], v3 offset:0x6800
	s_waitcnt lgkmcnt(6)
	v_mfma_f32_32x32x16_bf16 v[82:97], v[4:7], v[162:165], v[82:97]
	ds_read_b64_tr_b16 v[162:163], v3 offset:0x7000
	ds_read_b64_tr_b16 v[164:165], v3 offset:0x7800
	s_waitcnt lgkmcnt(6)
	v_mfma_f32_32x32x16_bf16 v[66:81], v[146:149], v[150:153], v[66:81]
	ds_read_b64_tr_b16 v[150:151], v3 offset:0x4200
	ds_read_b64_tr_b16 v[152:153], v3 offset:0x4a00
	s_waitcnt lgkmcnt(6)
	v_mfma_f32_32x32x16_bf16 v[66:81], v[12:15], v[154:157], v[66:81]
	ds_read_b64_tr_b16 v[154:155], v3 offset:0x5200
	ds_read_b64_tr_b16 v[156:157], v3 offset:0x5a00
	s_waitcnt lgkmcnt(6)
	v_mfma_f32_32x32x16_bf16 v[66:81], v[8:11], v[158:161], v[66:81]
	ds_read_b64_tr_b16 v[158:159], v3 offset:0x6200
	ds_read_b64_tr_b16 v[160:161], v3 offset:0x6a00
	s_waitcnt lgkmcnt(6)
	v_mfma_f32_32x32x16_bf16 v[66:81], v[4:7], v[162:165], v[66:81]
	ds_read_b64_tr_b16 v[162:163], v3 offset:0x7200
	ds_read_b64_tr_b16 v[164:165], v3 offset:0x7a00
	s_waitcnt lgkmcnt(6)
	v_mfma_f32_32x32x16_bf16 v[50:65], v[146:149], v[150:153], v[50:65]
	ds_read_b64_tr_b16 v[150:151], v3 offset:0x4400
	ds_read_b64_tr_b16 v[152:153], v3 offset:0x4c00
	s_waitcnt lgkmcnt(6)
	v_mfma_f32_32x32x16_bf16 v[50:65], v[12:15], v[154:157], v[50:65]
	ds_read_b64_tr_b16 v[154:155], v3 offset:0x5400
	ds_read_b64_tr_b16 v[156:157], v3 offset:0x5c00
	s_waitcnt lgkmcnt(6)
	v_mfma_f32_32x32x16_bf16 v[50:65], v[8:11], v[158:161], v[50:65]
	ds_read_b64_tr_b16 v[158:159], v3 offset:0x6400
	ds_read_b64_tr_b16 v[160:161], v3 offset:0x6c00
	s_waitcnt lgkmcnt(6)
	v_mfma_f32_32x32x16_bf16 v[50:65], v[4:7], v[162:165], v[50:65]
	ds_read_b64_tr_b16 v[162:163], v3 offset:0x7400
	ds_read_b64_tr_b16 v[164:165], v3 offset:0x7c00
	s_waitcnt lgkmcnt(6)
	v_mfma_f32_32x32x16_bf16 v[34:49], v[146:149], v[150:153], v[34:49]
	ds_read_b64_tr_b16 v[150:151], v3 offset:0x4600
	ds_read_b64_tr_b16 v[152:153], v3 offset:0x4e00
	s_waitcnt lgkmcnt(6)
	v_mfma_f32_32x32x16_bf16 v[34:49], v[12:15], v[154:157], v[34:49]
	ds_read_b64_tr_b16 v[154:155], v3 offset:0x5600
	ds_read_b64_tr_b16 v[156:157], v3 offset:0x5e00
	s_waitcnt lgkmcnt(6)
	v_mfma_f32_32x32x16_bf16 v[34:49], v[8:11], v[158:161], v[34:49]
	ds_read_b64_tr_b16 v[158:159], v3 offset:0x6600
	ds_read_b64_tr_b16 v[160:161], v3 offset:0x6e00
	s_waitcnt lgkmcnt(6)
	v_mfma_f32_32x32x16_bf16 v[34:49], v[4:7], v[162:165], v[34:49]
	ds_read_b64_tr_b16 v[162:163], v3 offset:0x7600
	ds_read_b64_tr_b16 v[164:165], v3 offset:0x7e00
	s_waitcnt lgkmcnt(6)
	v_mfma_f32_32x32x16_bf16 v[18:33], v[146:149], v[150:153], v[18:33]
	s_waitcnt lgkmcnt(4)
	v_mfma_f32_32x32x16_bf16 v[18:33], v[12:15], v[154:157], v[18:33]
	s_waitcnt lgkmcnt(2)
	v_mfma_f32_32x32x16_bf16 v[18:33], v[8:11], v[158:161], v[18:33]
	s_waitcnt lgkmcnt(0)
	v_mfma_f32_32x32x16_bf16 v[18:33], v[4:7], v[162:165], v[18:33]

.LBB0_389:
	v_mov_b32_e32 v82, 0
	ds_read_b128 v[4:7], v233 offset:32768
	ds_read_b128 v[8:11], v233 offset:40960
	ds_read_b128 v[12:15], v234 offset:32768
	v_mov_b32_e32 v83, v82
	v_mov_b32_e32 v84, v82
	v_mov_b32_e32 v85, v82
	v_mov_b32_e32 v86, v82
	v_mov_b32_e32 v87, v82
	v_mov_b32_e32 v88, v82
	v_mov_b32_e32 v89, v82
	v_mov_b32_e32 v90, v82
	v_mov_b32_e32 v91, v82
	v_mov_b32_e32 v92, v82
	v_mov_b32_e32 v93, v82
	v_mov_b32_e32 v94, v82
	v_mov_b32_e32 v95, v82
	v_mov_b32_e32 v96, v82
	v_mov_b32_e32 v97, v82
	v_add_u32_e32 v3, v225, v227
	s_cmp_le_i32 s81, s80
	s_waitcnt vmcnt(11) lgkmcnt(2)
	v_mfma_f32_32x32x16_bf16 v[98:113], v[4:7], v[126:129], v[82:97]
	ds_read_b128 v[4:7], v234 offset:40960
	s_waitcnt lgkmcnt(2)
	v_mfma_f32_32x32x16_bf16 v[82:97], v[8:11], v[126:129], v[82:97]
	ds_read_b128 v[8:11], v235 offset:32768
	s_waitcnt vmcnt(10) lgkmcnt(2)
	v_mfma_f32_32x32x16_bf16 v[98:113], v[12:15], v[130:133], v[98:113]
	ds_read_b128 v[12:15], v235 offset:40960
	s_waitcnt lgkmcnt(2)
	v_mfma_f32_32x32x16_bf16 v[82:97], v[4:7], v[130:133], v[82:97]
	ds_read_b128 v[4:7], v236 offset:32768
	s_waitcnt vmcnt(9) lgkmcnt(2)
	v_mfma_f32_32x32x16_bf16 v[98:113], v[8:11], v[138:141], v[98:113]
	ds_read_b128 v[8:11], v236 offset:40960
	s_waitcnt lgkmcnt(2)
	v_mfma_f32_32x32x16_bf16 v[82:97], v[12:15], v[138:141], v[82:97]
	ds_read_b128 v[12:15], v237 offset:32768
	s_waitcnt vmcnt(8) lgkmcnt(2)
	v_mfma_f32_32x32x16_bf16 v[98:113], v[4:7], v[142:145], v[98:113]
	ds_read_b128 v[4:7], v237 offset:40960
	s_waitcnt lgkmcnt(2)
	v_mfma_f32_32x32x16_bf16 v[82:97], v[8:11], v[142:145], v[82:97]
	ds_read_b128 v[8:11], v238 offset:32768
	s_waitcnt vmcnt(7) lgkmcnt(2)
	v_mfma_f32_32x32x16_bf16 v[98:113], v[12:15], v[146:149], v[98:113]
	ds_read_b128 v[12:15], v238 offset:40960
	s_waitcnt lgkmcnt(2)
	v_mfma_f32_32x32x16_bf16 v[82:97], v[4:7], v[146:149], v[82:97]
	ds_read_b128 v[4:7], v239 offset:32768
	s_waitcnt vmcnt(6) lgkmcnt(2)
	v_mfma_f32_32x32x16_bf16 v[98:113], v[8:11], v[150:153], v[98:113]
	ds_read_b128 v[8:11], v239 offset:40960
	s_waitcnt lgkmcnt(2)
	v_mfma_f32_32x32x16_bf16 v[82:97], v[12:15], v[150:153], v[82:97]
	ds_read_b128 v[12:15], v240 offset:32768
	s_waitcnt vmcnt(5) lgkmcnt(2)
	v_mfma_f32_32x32x16_bf16 v[98:113], v[4:7], v[154:157], v[98:113]
	ds_read_b128 v[4:7], v240 offset:40960
	s_waitcnt lgkmcnt(2)
	v_mfma_f32_32x32x16_bf16 v[82:97], v[8:11], v[154:157], v[82:97]
	ds_read_b128 v[8:11], v3
	s_waitcnt vmcnt(4) lgkmcnt(2)
	v_mfma_f32_32x32x16_bf16 v[98:113], v[12:15], v[158:161], v[98:113]
	ds_read_b128 v[12:15], v3 offset:4096
	v_add_u32_e32 v3, v225, v228
	s_waitcnt lgkmcnt(2)
	v_mfma_f32_32x32x16_bf16 v[82:97], v[4:7], v[158:161], v[82:97]
	ds_read_b128 v[4:7], v3
	s_waitcnt vmcnt(3) lgkmcnt(2)
	v_mfma_f32_32x32x16_bf16 v[98:113], v[8:11], v[162:165], v[98:113]
	ds_read_b128 v[8:11], v3 offset:4096
	v_add_u32_e32 v3, v225, v229
	s_waitcnt lgkmcnt(2)
	v_mfma_f32_32x32x16_bf16 v[82:97], v[12:15], v[162:165], v[82:97]
	ds_read_b128 v[12:15], v3
	s_waitcnt vmcnt(2) lgkmcnt(2)
	v_mfma_f32_32x32x16_bf16 v[98:113], v[4:7], v[166:169], v[98:113]
	ds_read_b128 v[4:7], v3 offset:4096
	v_add_u32_e32 v3, v225, v230
	s_waitcnt lgkmcnt(2)
	v_mfma_f32_32x32x16_bf16 v[82:97], v[8:11], v[166:169], v[82:97]
	ds_read_b128 v[8:11], v3
	s_waitcnt vmcnt(1) lgkmcnt(2)
	v_mfma_f32_32x32x16_bf16 v[98:113], v[12:15], v[170:173], v[98:113]
	ds_read_b128 v[12:15], v3 offset:4096
	s_waitcnt lgkmcnt(2)
	v_mfma_f32_32x32x16_bf16 v[82:97], v[4:7], v[170:173], v[82:97]
	s_waitcnt vmcnt(0) lgkmcnt(1)
	v_mfma_f32_32x32x16_bf16 v[98:113], v[8:11], v[174:177], v[98:113]
	s_waitcnt lgkmcnt(0)
	v_mfma_f32_32x32x16_bf16 v[82:97], v[12:15], v[174:177], v[82:97]
	s_cbranch_scc1 .LBB0_391
	v_cmp_gt_i32_e64 s[68:69], 26, v218
	v_cmp_gt_i32_e64 s[70:71], 27, v218
	v_cmp_gt_i32_e64 s[66:67], 25, v218
	s_and_b64 s[68:69], s[70:71], s[68:69]
	v_cmp_gt_i32_e64 s[64:65], 24, v218
	s_and_b64 s[66:67], s[68:69], s[66:67]
	v_cmp_gt_i32_e64 s[62:63], 19, v218
	s_and_b64 s[64:65], s[66:67], s[64:65]
	v_cmp_gt_i32_e64 s[60:61], 18, v218
	s_and_b64 s[62:63], s[64:65], s[62:63]
	v_cmp_gt_i32_e64 s[58:59], 17, v218
	s_and_b64 s[60:61], s[62:63], s[60:61]
	v_cmp_gt_i32_e64 s[56:57], 16, v218
	s_and_b64 s[58:59], s[60:61], s[58:59]
	v_cmp_gt_i32_e64 s[54:55], 11, v218
	s_and_b64 s[56:57], s[58:59], s[56:57]
	v_cmp_gt_i32_e64 s[52:53], 10, v218
	s_and_b64 s[54:55], s[56:57], s[54:55]
	v_cmp_gt_i32_e64 s[50:51], 9, v218
	s_and_b64 s[52:53], s[54:55], s[52:53]
	v_cmp_gt_i32_e64 s[48:49], 8, v218
	s_and_b64 s[50:51], s[52:53], s[50:51]
	v_cmp_gt_i32_e64 s[46:47], 3, v218
	s_and_b64 s[48:49], s[50:51], s[48:49]
	v_cmp_gt_i32_e64 s[44:45], 2, v218
	s_and_b64 s[46:47], s[48:49], s[46:47]
	v_cmp_gt_i32_e64 s[42:43], 1, v218
	s_and_b64 s[44:45], s[46:47], s[44:45]
	v_cmp_gt_i32_e64 s[40:41], 0, v218
	s_and_b64 s[42:43], s[44:45], s[42:43]
	s_and_b64 s[40:41], s[42:43], s[40:41]
	v_cmp_gt_i32_e64 s[36:37], 58, v218
	v_cndmask_b32_e64 v98, v98, v210, s[40:41]
	v_cmp_gt_i32_e64 s[40:41], 59, v218
	v_cmp_gt_i32_e64 s[34:35], 57, v218
	s_and_b64 s[36:37], s[40:41], s[36:37]
	v_cmp_gt_i32_e64 s[30:31], 56, v218
	s_and_b64 s[34:35], s[36:37], s[34:35]
	v_cmp_gt_i32_e64 s[28:29], 51, v218
	s_and_b64 s[30:31], s[34:35], s[30:31]
	v_cmp_gt_i32_e64 s[26:27], 50, v218
	s_and_b64 s[28:29], s[30:31], s[28:29]
	v_cmp_gt_i32_e64 s[24:25], 49, v218
	s_and_b64 s[26:27], s[28:29], s[26:27]
	v_cmp_gt_i32_e64 s[22:23], 48, v218
	s_and_b64 s[24:25], s[26:27], s[24:25]
	v_cmp_gt_i32_e64 s[20:21], 43, v218
	s_and_b64 s[22:23], s[24:25], s[22:23]
	v_cmp_gt_i32_e64 s[18:19], 42, v218
	s_and_b64 s[20:21], s[22:23], s[20:21]
	v_cmp_gt_i32_e64 s[16:17], 41, v218
	s_and_b64 s[18:19], s[20:21], s[18:19]
	v_cmp_gt_i32_e64 s[14:15], 40, v218
	s_and_b64 s[16:17], s[18:19], s[16:17]
	v_cmp_gt_i32_e64 s[12:13], 35, v218
	s_and_b64 s[14:15], s[16:17], s[14:15]
	v_cmp_gt_i32_e64 s[10:11], 34, v218
	s_and_b64 s[12:13], s[14:15], s[12:13]
	v_cmp_gt_i32_e64 s[8:9], 33, v218
	s_and_b64 s[10:11], s[12:13], s[10:11]
	v_cmp_gt_i32_e32 vcc, 32, v218
	s_and_b64 s[8:9], s[10:11], s[8:9]
	s_and_b64 vcc, s[8:9], vcc
	v_cndmask_b32_e64 v113, v113, v210, s[70:71]
	v_cndmask_b32_e64 v112, v112, v210, s[68:69]
	v_cndmask_b32_e64 v111, v111, v210, s[66:67]
	v_cndmask_b32_e64 v110, v110, v210, s[64:65]
	v_cndmask_b32_e64 v109, v109, v210, s[62:63]
	v_cndmask_b32_e64 v108, v108, v210, s[60:61]
	v_cndmask_b32_e64 v107, v107, v210, s[58:59]
	v_cndmask_b32_e64 v106, v106, v210, s[56:57]
	v_cndmask_b32_e64 v105, v105, v210, s[54:55]
	v_cndmask_b32_e64 v104, v104, v210, s[52:53]
	v_cndmask_b32_e64 v103, v103, v210, s[50:51]
	v_cndmask_b32_e64 v102, v102, v210, s[48:49]
	v_cndmask_b32_e64 v101, v101, v210, s[46:47]
	v_cndmask_b32_e64 v100, v100, v210, s[44:45]
	v_cndmask_b32_e64 v99, v99, v210, s[42:43]
	v_cndmask_b32_e64 v97, v97, v210, s[40:41]
	v_cndmask_b32_e64 v96, v96, v210, s[36:37]
	v_cndmask_b32_e64 v95, v95, v210, s[34:35]
	v_cndmask_b32_e64 v94, v94, v210, s[30:31]
	v_cndmask_b32_e64 v93, v93, v210, s[28:29]
	v_cndmask_b32_e64 v92, v92, v210, s[26:27]
	v_cndmask_b32_e64 v91, v91, v210, s[24:25]
	v_cndmask_b32_e64 v90, v90, v210, s[22:23]
	v_cndmask_b32_e64 v89, v89, v210, s[20:21]
	v_cndmask_b32_e64 v88, v88, v210, s[18:19]
	v_cndmask_b32_e64 v87, v87, v210, s[16:17]
	v_cndmask_b32_e64 v86, v86, v210, s[14:15]
	v_cndmask_b32_e64 v85, v85, v210, s[12:13]
	v_cndmask_b32_e64 v84, v84, v210, s[10:11]
	v_cndmask_b32_e64 v83, v83, v210, s[8:9]
	v_cndmask_b32_e32 v82, v82, v210, vcc

.LBB0_395:
	ds_read_b64_tr_b16 v[86:87], v223 offset:0
	ds_read_b64_tr_b16 v[88:89], v223 offset:0x800
	ds_read_b64_tr_b16 v[90:91], v223 offset:0x1000
	ds_read_b64_tr_b16 v[92:93], v223 offset:0x1800
	ds_read_b64_tr_b16 v[94:95], v223 offset:0x2000
	ds_read_b64_tr_b16 v[96:97], v223 offset:0x2800
	ds_read_b64_tr_b16 v[98:99], v223 offset:0x3000
	ds_read_b64_tr_b16 v[100:101], v223 offset:0x3800
	s_waitcnt lgkmcnt(0)
	v_add_f32_e32 v16, v16, v17
	v_fmac_f32_e32 v16, v241, v3
	v_mfma_f32_32x32x16_bf16 v[66:81], v[4:7], v[86:89], v[66:81]
	ds_read_b64_tr_b16 v[86:87], v223 offset:0x200
	ds_read_b64_tr_b16 v[88:89], v223 offset:0xa00
	v_mfma_f32_32x32x16_bf16 v[66:81], v[8:11], v[90:93], v[66:81]
	ds_read_b64_tr_b16 v[90:91], v223 offset:0x1200
	ds_read_b64_tr_b16 v[92:93], v223 offset:0x1a00
	v_mfma_f32_32x32x16_bf16 v[66:81], v[12:15], v[94:97], v[66:81]
	ds_read_b64_tr_b16 v[94:95], v223 offset:0x2200
	ds_read_b64_tr_b16 v[96:97], v223 offset:0x2a00
	v_mfma_f32_32x32x16_bf16 v[66:81], v[82:85], v[98:101], v[66:81]
	ds_read_b64_tr_b16 v[98:99], v223 offset:0x3200
	ds_read_b64_tr_b16 v[100:101], v223 offset:0x3a00
	s_waitcnt lgkmcnt(6)
	v_mfma_f32_32x32x16_bf16 v[50:65], v[4:7], v[86:89], v[50:65]
	ds_read_b64_tr_b16 v[86:87], v223 offset:0x400
	ds_read_b64_tr_b16 v[88:89], v223 offset:0xc00
	s_waitcnt lgkmcnt(6)
	v_mfma_f32_32x32x16_bf16 v[50:65], v[8:11], v[90:93], v[50:65]
	ds_read_b64_tr_b16 v[90:91], v223 offset:0x1400
	ds_read_b64_tr_b16 v[92:93], v223 offset:0x1c00
	s_waitcnt lgkmcnt(6)
	v_mfma_f32_32x32x16_bf16 v[50:65], v[12:15], v[94:97], v[50:65]
	ds_read_b64_tr_b16 v[94:95], v223 offset:0x2400
	ds_read_b64_tr_b16 v[96:97], v223 offset:0x2c00
	s_waitcnt lgkmcnt(6)
	v_mfma_f32_32x32x16_bf16 v[50:65], v[82:85], v[98:101], v[50:65]
	ds_read_b64_tr_b16 v[98:99], v223 offset:0x3400
	ds_read_b64_tr_b16 v[100:101], v223 offset:0x3c00
	s_waitcnt lgkmcnt(6)
	v_mfma_f32_32x32x16_bf16 v[34:49], v[4:7], v[86:89], v[34:49]
	ds_read_b64_tr_b16 v[86:87], v223 offset:0x600
	ds_read_b64_tr_b16 v[88:89], v223 offset:0xe00
	s_waitcnt lgkmcnt(6)
	v_mfma_f32_32x32x16_bf16 v[34:49], v[8:11], v[90:93], v[34:49]
	ds_read_b64_tr_b16 v[90:91], v223 offset:0x1600
	ds_read_b64_tr_b16 v[92:93], v223 offset:0x1e00
	s_waitcnt lgkmcnt(6)
	v_mfma_f32_32x32x16_bf16 v[34:49], v[12:15], v[94:97], v[34:49]
	ds_read_b64_tr_b16 v[94:95], v223 offset:0x2600
	ds_read_b64_tr_b16 v[96:97], v223 offset:0x2e00
	s_waitcnt lgkmcnt(6)
	v_mfma_f32_32x32x16_bf16 v[34:49], v[82:85], v[98:101], v[34:49]
	ds_read_b64_tr_b16 v[98:99], v223 offset:0x3600
	ds_read_b64_tr_b16 v[100:101], v223 offset:0x3e00
	s_waitcnt lgkmcnt(6)
	v_mfma_f32_32x32x16_bf16 v[18:33], v[4:7], v[86:89], v[18:33]
	v_mov_b32_e32 v241, v16
	s_waitcnt lgkmcnt(4)
	v_mfma_f32_32x32x16_bf16 v[18:33], v[8:11], v[90:93], v[18:33]
	s_waitcnt lgkmcnt(2)
	v_mfma_f32_32x32x16_bf16 v[18:33], v[12:15], v[94:97], v[18:33]
	s_waitcnt lgkmcnt(0)
	v_mfma_f32_32x32x16_bf16 v[18:33], v[82:85], v[98:101], v[18:33]
	s_andn2_b64 vcc, exec, s[82:83]
	s_cbranch_vccz .LBB0_384
	s_branch .LBB0_385

.LBB0_397:
	v_mov_b32_e32 v82, 0
	ds_read_b128 v[4:7], v233 offset:49152
	ds_read_b128 v[8:11], v233 offset:57344
	ds_read_b128 v[12:15], v234 offset:49152
	v_mov_b32_e32 v83, v82
	v_mov_b32_e32 v84, v82
	v_mov_b32_e32 v85, v82
	v_mov_b32_e32 v86, v82
	v_mov_b32_e32 v87, v82
	v_mov_b32_e32 v88, v82
	v_mov_b32_e32 v89, v82
	v_mov_b32_e32 v90, v82
	v_mov_b32_e32 v91, v82
	v_mov_b32_e32 v92, v82
	v_mov_b32_e32 v93, v82
	v_mov_b32_e32 v94, v82
	v_mov_b32_e32 v95, v82
	v_mov_b32_e32 v96, v82
	v_mov_b32_e32 v97, v82
	v_add_u32_e32 v3, v231, v227
	s_add_i32 s0, s81, 64
	s_waitcnt vmcnt(11) lgkmcnt(2)
	v_mfma_f32_32x32x16_bf16 v[98:113], v[4:7], v[126:129], v[82:97]
	ds_read_b128 v[4:7], v234 offset:57344
	s_cmp_le_i32 s0, s80
	s_waitcnt lgkmcnt(2)
	v_mfma_f32_32x32x16_bf16 v[82:97], v[8:11], v[126:129], v[82:97]
	ds_read_b128 v[8:11], v235 offset:49152
	s_waitcnt vmcnt(10) lgkmcnt(2)
	v_mfma_f32_32x32x16_bf16 v[98:113], v[12:15], v[130:133], v[98:113]
	ds_read_b128 v[12:15], v235 offset:57344
	s_waitcnt lgkmcnt(2)
	v_mfma_f32_32x32x16_bf16 v[82:97], v[4:7], v[130:133], v[82:97]
	ds_read_b128 v[4:7], v236 offset:49152
	s_waitcnt vmcnt(9) lgkmcnt(2)
	v_mfma_f32_32x32x16_bf16 v[98:113], v[8:11], v[138:141], v[98:113]
	ds_read_b128 v[8:11], v236 offset:57344
	s_waitcnt lgkmcnt(2)
	v_mfma_f32_32x32x16_bf16 v[82:97], v[12:15], v[138:141], v[82:97]
	ds_read_b128 v[12:15], v237 offset:49152
	s_waitcnt vmcnt(8) lgkmcnt(2)
	v_mfma_f32_32x32x16_bf16 v[98:113], v[4:7], v[142:145], v[98:113]
	ds_read_b128 v[4:7], v237 offset:57344
	s_waitcnt lgkmcnt(2)
	v_mfma_f32_32x32x16_bf16 v[82:97], v[8:11], v[142:145], v[82:97]
	ds_read_b128 v[8:11], v238 offset:49152
	s_waitcnt vmcnt(7) lgkmcnt(2)
	v_mfma_f32_32x32x16_bf16 v[98:113], v[12:15], v[146:149], v[98:113]
	ds_read_b128 v[12:15], v238 offset:57344
	s_waitcnt lgkmcnt(2)
	v_mfma_f32_32x32x16_bf16 v[82:97], v[4:7], v[146:149], v[82:97]
	ds_read_b128 v[4:7], v239 offset:49152
	s_waitcnt vmcnt(6) lgkmcnt(2)
	v_mfma_f32_32x32x16_bf16 v[98:113], v[8:11], v[150:153], v[98:113]
	ds_read_b128 v[8:11], v239 offset:57344
	s_waitcnt lgkmcnt(2)
	v_mfma_f32_32x32x16_bf16 v[82:97], v[12:15], v[150:153], v[82:97]
	ds_read_b128 v[12:15], v240 offset:49152
	s_waitcnt vmcnt(5) lgkmcnt(2)
	v_mfma_f32_32x32x16_bf16 v[98:113], v[4:7], v[154:157], v[98:113]
	ds_read_b128 v[4:7], v240 offset:57344
	s_waitcnt lgkmcnt(2)
	v_mfma_f32_32x32x16_bf16 v[82:97], v[8:11], v[154:157], v[82:97]
	ds_read_b128 v[8:11], v3
	s_waitcnt vmcnt(4) lgkmcnt(2)
	v_mfma_f32_32x32x16_bf16 v[98:113], v[12:15], v[158:161], v[98:113]
	ds_read_b128 v[12:15], v3 offset:4096
	v_add_u32_e32 v3, v231, v228
	s_waitcnt lgkmcnt(2)
	v_mfma_f32_32x32x16_bf16 v[82:97], v[4:7], v[158:161], v[82:97]
	ds_read_b128 v[4:7], v3
	s_waitcnt vmcnt(3) lgkmcnt(2)
	v_mfma_f32_32x32x16_bf16 v[98:113], v[8:11], v[162:165], v[98:113]
	ds_read_b128 v[8:11], v3 offset:4096
	v_add_u32_e32 v3, v231, v229
	s_waitcnt lgkmcnt(2)
	v_mfma_f32_32x32x16_bf16 v[82:97], v[12:15], v[162:165], v[82:97]
	ds_read_b128 v[12:15], v3
	s_waitcnt vmcnt(2) lgkmcnt(2)
	v_mfma_f32_32x32x16_bf16 v[98:113], v[4:7], v[166:169], v[98:113]
	ds_read_b128 v[4:7], v3 offset:4096
	v_add_u32_e32 v3, v231, v230
	s_waitcnt lgkmcnt(2)
	v_mfma_f32_32x32x16_bf16 v[82:97], v[8:11], v[166:169], v[82:97]
	ds_read_b128 v[8:11], v3
	s_waitcnt vmcnt(1) lgkmcnt(2)
	v_mfma_f32_32x32x16_bf16 v[98:113], v[12:15], v[170:173], v[98:113]
	ds_read_b128 v[12:15], v3 offset:4096
	s_waitcnt lgkmcnt(2)
	v_mfma_f32_32x32x16_bf16 v[82:97], v[4:7], v[170:173], v[82:97]
	s_waitcnt vmcnt(0) lgkmcnt(1)
	v_mfma_f32_32x32x16_bf16 v[98:113], v[8:11], v[174:177], v[98:113]
	s_waitcnt lgkmcnt(0)
	v_mfma_f32_32x32x16_bf16 v[82:97], v[12:15], v[174:177], v[82:97]
	s_cbranch_scc1 .LBB0_399
	v_subrev_u32_e32 v3, 64, v218
	v_cmp_gt_i32_e64 s[68:69], 26, v3
	v_cmp_gt_i32_e64 s[70:71], 27, v3
	v_cmp_gt_i32_e64 s[66:67], 25, v3
	s_and_b64 s[68:69], s[70:71], s[68:69]
	v_cmp_gt_i32_e64 s[64:65], 24, v3
	s_and_b64 s[66:67], s[68:69], s[66:67]
	v_cmp_gt_i32_e64 s[62:63], 19, v3
	s_and_b64 s[64:65], s[66:67], s[64:65]
	v_cmp_gt_i32_e64 s[60:61], 18, v3
	s_and_b64 s[62:63], s[64:65], s[62:63]
	v_cmp_gt_i32_e64 s[58:59], 17, v3
	s_and_b64 s[60:61], s[62:63], s[60:61]
	v_cmp_gt_i32_e64 s[56:57], 16, v3
	s_and_b64 s[58:59], s[60:61], s[58:59]
	v_cmp_gt_i32_e64 s[54:55], 11, v3
	s_and_b64 s[56:57], s[58:59], s[56:57]
	v_cmp_gt_i32_e64 s[52:53], 10, v3
	s_and_b64 s[54:55], s[56:57], s[54:55]
	v_cmp_gt_i32_e64 s[50:51], 9, v3
	s_and_b64 s[52:53], s[54:55], s[52:53]
	v_cmp_gt_i32_e64 s[48:49], 8, v3
	s_and_b64 s[50:51], s[52:53], s[50:51]
	v_cmp_gt_i32_e64 s[46:47], 3, v3
	s_and_b64 s[48:49], s[50:51], s[48:49]
	v_cmp_gt_i32_e64 s[44:45], 2, v3
	s_and_b64 s[46:47], s[48:49], s[46:47]
	v_cmp_gt_i32_e64 s[42:43], 1, v3
	s_and_b64 s[44:45], s[46:47], s[44:45]
	v_cmp_gt_i32_e64 s[40:41], 0, v3
	s_and_b64 s[42:43], s[44:45], s[42:43]
	s_and_b64 s[40:41], s[42:43], s[40:41]
	v_cmp_gt_i32_e64 s[36:37], 58, v3
	v_cndmask_b32_e64 v98, v98, v210, s[40:41]
	v_cmp_gt_i32_e64 s[40:41], 59, v3
	v_cmp_gt_i32_e64 s[34:35], 57, v3
	s_and_b64 s[36:37], s[40:41], s[36:37]
	v_cmp_gt_i32_e64 s[30:31], 56, v3
	s_and_b64 s[34:35], s[36:37], s[34:35]
	v_cmp_gt_i32_e64 s[28:29], 51, v3
	s_and_b64 s[30:31], s[34:35], s[30:31]
	v_cmp_gt_i32_e64 s[26:27], 50, v3
	s_and_b64 s[28:29], s[30:31], s[28:29]
	v_cmp_gt_i32_e64 s[24:25], 49, v3
	s_and_b64 s[26:27], s[28:29], s[26:27]
	v_cmp_gt_i32_e64 s[22:23], 48, v3
	s_and_b64 s[24:25], s[26:27], s[24:25]
	v_cmp_gt_i32_e64 s[20:21], 43, v3
	s_and_b64 s[22:23], s[24:25], s[22:23]
	v_cmp_gt_i32_e64 s[18:19], 42, v3
	s_and_b64 s[20:21], s[22:23], s[20:21]
	v_cmp_gt_i32_e64 s[16:17], 41, v3
	s_and_b64 s[18:19], s[20:21], s[18:19]
	v_cmp_gt_i32_e64 s[14:15], 40, v3
	s_and_b64 s[16:17], s[18:19], s[16:17]
	v_cmp_gt_i32_e64 s[12:13], 35, v3
	s_and_b64 s[14:15], s[16:17], s[14:15]
	v_cmp_gt_i32_e64 s[10:11], 34, v3
	s_and_b64 s[12:13], s[14:15], s[12:13]
	v_cmp_gt_i32_e64 s[8:9], 33, v3
	s_and_b64 s[10:11], s[12:13], s[10:11]
	v_cmp_gt_i32_e32 vcc, 32, v3
	s_and_b64 s[8:9], s[10:11], s[8:9]
	s_and_b64 vcc, s[8:9], vcc
	v_cndmask_b32_e64 v113, v113, v210, s[70:71]
	v_cndmask_b32_e64 v112, v112, v210, s[68:69]
	v_cndmask_b32_e64 v111, v111, v210, s[66:67]
	v_cndmask_b32_e64 v110, v110, v210, s[64:65]
	v_cndmask_b32_e64 v109, v109, v210, s[62:63]
	v_cndmask_b32_e64 v108, v108, v210, s[60:61]
	v_cndmask_b32_e64 v107, v107, v210, s[58:59]
	v_cndmask_b32_e64 v106, v106, v210, s[56:57]
	v_cndmask_b32_e64 v105, v105, v210, s[54:55]
	v_cndmask_b32_e64 v104, v104, v210, s[52:53]
	v_cndmask_b32_e64 v103, v103, v210, s[50:51]
	v_cndmask_b32_e64 v102, v102, v210, s[48:49]
	v_cndmask_b32_e64 v101, v101, v210, s[46:47]
	v_cndmask_b32_e64 v100, v100, v210, s[44:45]
	v_cndmask_b32_e64 v99, v99, v210, s[42:43]
	v_cndmask_b32_e64 v97, v97, v210, s[40:41]
	v_cndmask_b32_e64 v96, v96, v210, s[36:37]
	v_cndmask_b32_e64 v95, v95, v210, s[34:35]
	v_cndmask_b32_e64 v94, v94, v210, s[30:31]
	v_cndmask_b32_e64 v93, v93, v210, s[28:29]
	v_cndmask_b32_e64 v92, v92, v210, s[26:27]
	v_cndmask_b32_e64 v91, v91, v210, s[24:25]
	v_cndmask_b32_e64 v90, v90, v210, s[22:23]
	v_cndmask_b32_e64 v89, v89, v210, s[20:21]
	v_cndmask_b32_e64 v88, v88, v210, s[18:19]
	v_cndmask_b32_e64 v87, v87, v210, s[16:17]
	v_cndmask_b32_e64 v86, v86, v210, s[14:15]
	v_cndmask_b32_e64 v85, v85, v210, s[12:13]
	v_cndmask_b32_e64 v84, v84, v210, s[10:11]
	v_cndmask_b32_e64 v83, v83, v210, s[8:9]
	v_cndmask_b32_e32 v82, v82, v210, vcc

.LBB0_403:
	ds_read_b64_tr_b16 v[86:87], v223 offset:0x4000
	ds_read_b64_tr_b16 v[88:89], v223 offset:0x4800
	ds_read_b64_tr_b16 v[90:91], v223 offset:0x5000
	ds_read_b64_tr_b16 v[92:93], v223 offset:0x5800
	ds_read_b64_tr_b16 v[94:95], v223 offset:0x6000
	ds_read_b64_tr_b16 v[96:97], v223 offset:0x6800
	ds_read_b64_tr_b16 v[98:99], v223 offset:0x7000
	ds_read_b64_tr_b16 v[100:101], v223 offset:0x7800
	s_waitcnt lgkmcnt(0)
	v_add_f32_e32 v16, v16, v17
	v_fmac_f32_e32 v16, v241, v3
	v_mfma_f32_32x32x16_bf16 v[66:81], v[4:7], v[86:89], v[66:81]
	ds_read_b64_tr_b16 v[86:87], v223 offset:0x4200
	ds_read_b64_tr_b16 v[88:89], v223 offset:0x4a00
	v_mfma_f32_32x32x16_bf16 v[66:81], v[8:11], v[90:93], v[66:81]
	ds_read_b64_tr_b16 v[90:91], v223 offset:0x5200
	ds_read_b64_tr_b16 v[92:93], v223 offset:0x5a00
	v_mfma_f32_32x32x16_bf16 v[66:81], v[12:15], v[94:97], v[66:81]
	ds_read_b64_tr_b16 v[94:95], v223 offset:0x6200
	ds_read_b64_tr_b16 v[96:97], v223 offset:0x6a00
	v_mfma_f32_32x32x16_bf16 v[66:81], v[82:85], v[98:101], v[66:81]
	ds_read_b64_tr_b16 v[98:99], v223 offset:0x7200
	ds_read_b64_tr_b16 v[100:101], v223 offset:0x7a00
	s_waitcnt lgkmcnt(6)
	v_mfma_f32_32x32x16_bf16 v[50:65], v[4:7], v[86:89], v[50:65]
	ds_read_b64_tr_b16 v[86:87], v223 offset:0x4400
	ds_read_b64_tr_b16 v[88:89], v223 offset:0x4c00
	s_waitcnt lgkmcnt(6)
	v_mfma_f32_32x32x16_bf16 v[50:65], v[8:11], v[90:93], v[50:65]
	ds_read_b64_tr_b16 v[90:91], v223 offset:0x5400
	ds_read_b64_tr_b16 v[92:93], v223 offset:0x5c00
	s_waitcnt lgkmcnt(6)
	v_mfma_f32_32x32x16_bf16 v[50:65], v[12:15], v[94:97], v[50:65]
	ds_read_b64_tr_b16 v[94:95], v223 offset:0x6400
	ds_read_b64_tr_b16 v[96:97], v223 offset:0x6c00
	s_waitcnt lgkmcnt(6)
	v_mfma_f32_32x32x16_bf16 v[50:65], v[82:85], v[98:101], v[50:65]
	ds_read_b64_tr_b16 v[98:99], v223 offset:0x7400
	ds_read_b64_tr_b16 v[100:101], v223 offset:0x7c00
	s_waitcnt lgkmcnt(6)
	v_mfma_f32_32x32x16_bf16 v[34:49], v[4:7], v[86:89], v[34:49]
	ds_read_b64_tr_b16 v[86:87], v223 offset:0x4600
	ds_read_b64_tr_b16 v[88:89], v223 offset:0x4e00
	s_waitcnt lgkmcnt(6)
	v_mfma_f32_32x32x16_bf16 v[34:49], v[8:11], v[90:93], v[34:49]
	ds_read_b64_tr_b16 v[90:91], v223 offset:0x5600
	ds_read_b64_tr_b16 v[92:93], v223 offset:0x5e00
	s_waitcnt lgkmcnt(6)
	v_mfma_f32_32x32x16_bf16 v[34:49], v[12:15], v[94:97], v[34:49]
	ds_read_b64_tr_b16 v[94:95], v223 offset:0x6600
	ds_read_b64_tr_b16 v[96:97], v223 offset:0x6e00
	s_waitcnt lgkmcnt(6)
	v_mfma_f32_32x32x16_bf16 v[34:49], v[82:85], v[98:101], v[34:49]
	ds_read_b64_tr_b16 v[98:99], v223 offset:0x7600
	ds_read_b64_tr_b16 v[100:101], v223 offset:0x7e00
	s_waitcnt lgkmcnt(6)
	v_mfma_f32_32x32x16_bf16 v[18:33], v[4:7], v[86:89], v[18:33]
	v_mov_b32_e32 v241, v16
	s_waitcnt lgkmcnt(4)
	v_mfma_f32_32x32x16_bf16 v[18:33], v[8:11], v[90:93], v[18:33]
	s_waitcnt lgkmcnt(2)
	v_mfma_f32_32x32x16_bf16 v[18:33], v[12:15], v[94:97], v[18:33]
	s_waitcnt lgkmcnt(0)
	v_mfma_f32_32x32x16_bf16 v[18:33], v[82:85], v[98:101], v[18:33]
	s_andn2_b64 vcc, exec, s[84:85]
	s_cbranch_vccnz .LBB0_380

.LBB0_622:
	v_bitop3_b32 v13, v213, v13, 2 bitop3:0x36
	v_lshlrev_b32_e32 v180, 4, v13
	s_andn2_b64 vcc, exec, s[16:17]
	v_mov_b32_e32 v115, 0
	s_cbranch_vccnz .LBB0_625
	s_add_i32 s1, s5, -1
	s_add_u32 s35, s35, 0x80
	v_lshl_add_u64 v[168:169], s[14:15], 0, v[6:7]
	s_addc_u32 s19, s19, 0
	s_lshl_b64 s[14:15], s[46:47], 9
	s_or_b32 s16, s14, 48
	s_mul_i32 s17, s16, s13
	s_mul_hi_u32 s39, s16, s12
	s_add_i32 s17, s39, s17
	s_mul_i32 s15, s15, s12
	v_lshl_add_u64 v[166:167], v[8:9], 0, v[6:7]
	s_add_i32 s17, s17, s15
	s_mul_i32 s16, s16, s12
	v_add_u32_e32 v6, s33, v11
	v_mul_lo_u32 v8, s38, v6
	s_add_u32 s16, s35, s16
	v_add_u32_e32 v6, v8, v12
	v_mov_b32_e32 v7, v2
	s_addc_u32 s17, s19, s17
	v_lshl_add_u64 v[170:171], s[16:17], 0, v[6:7]
	s_lshl_b64 s[16:17], s[2:3], 9
	s_or_b32 s3, s16, 48
	s_mul_i32 s17, s17, s12
	s_mul_i32 s33, s3, s13
	v_mov_b32_e32 v9, s12
	s_add_i32 s33, s33, s17
	v_mad_u64_u32 v[6:7], s[38:39], s3, v9, v[6:7]
	v_lshl_add_u64 v[4:5], v[4:5], 0, s[66:67]
	v_add_u32_e32 v7, s33, v7
	s_or_b32 s3, s16, 32
	v_lshl_add_u64 v[172:173], v[4:5], 0, v[6:7]
	v_add_u32_e32 v6, v8, v10
	v_mov_b32_e32 v7, v2
	s_mul_i32 s16, s3, s13
	s_add_i32 s33, s16, s17
	v_mad_u64_u32 v[8:9], s[16:17], s3, v9, v[6:7]
	s_or_b32 s3, s14, 32
	s_mul_i32 s13, s3, s13
	s_mul_hi_u32 s14, s3, s12
	s_add_i32 s13, s14, s13
	s_add_i32 s13, s13, s15
	s_mul_i32 s3, s3, s12
	v_add_u32_e32 v9, s33, v9
	s_add_u32 s12, s35, s3
	v_lshl_add_u64 v[174:175], v[4:5], 0, v[8:9]
	s_addc_u32 s13, s19, s13
	v_mov_b32_e32 v4, 0
	v_lshl_add_u64 v[176:177], s[12:13], 0, v[6:7]
	s_mov_b32 s3, 1
	s_mov_b32 s14, 0
	s_mov_b64 s[12:13], 0
	v_mov_b32_e32 v5, v4
	v_mov_b32_e32 v6, v4
	v_mov_b32_e32 v7, v4
	v_mov_b32_e32 v8, v4
	v_mov_b32_e32 v9, v4
	v_mov_b32_e32 v10, v4
	v_mov_b32_e32 v11, v4
	v_mov_b32_e32 v12, v4
	v_mov_b32_e32 v13, v4
	v_mov_b32_e32 v14, v4
	v_mov_b32_e32 v15, v4
	v_mov_b32_e32 v16, v4
	v_mov_b32_e32 v17, v4
	v_mov_b32_e32 v18, v4
	v_mov_b32_e32 v19, v4
	v_mov_b32_e32 v20, v4
	v_mov_b32_e32 v21, v4
	v_mov_b32_e32 v22, v4
	v_mov_b32_e32 v23, v4
	v_mov_b32_e32 v24, v4
	v_mov_b32_e32 v25, v4
	v_mov_b32_e32 v26, v4
	v_mov_b32_e32 v27, v4
	v_mov_b32_e32 v28, v4
	v_mov_b32_e32 v29, v4
	v_mov_b32_e32 v30, v4
	v_mov_b32_e32 v31, v4
	v_mov_b32_e32 v32, v4
	v_mov_b32_e32 v33, v4
	v_mov_b32_e32 v34, v4
	v_mov_b32_e32 v35, v4
	v_mov_b32_e32 v36, v4
	v_mov_b32_e32 v37, v4
	v_mov_b32_e32 v38, v4
	v_mov_b32_e32 v39, v4
	v_mov_b32_e32 v40, v4
	v_mov_b32_e32 v41, v4
	v_mov_b32_e32 v42, v4
	v_mov_b32_e32 v43, v4
	v_mov_b32_e32 v44, v4
	v_mov_b32_e32 v45, v4
	v_mov_b32_e32 v46, v4
	v_mov_b32_e32 v47, v4
	v_mov_b32_e32 v48, v4
	v_mov_b32_e32 v49, v4
	v_mov_b32_e32 v50, v4
	v_mov_b32_e32 v51, v4
	v_mov_b32_e32 v52, v4
	v_mov_b32_e32 v53, v4
	v_mov_b32_e32 v54, v4
	v_mov_b32_e32 v55, v4
	v_mov_b32_e32 v56, v4
	v_mov_b32_e32 v57, v4
	v_mov_b32_e32 v58, v4
	v_mov_b32_e32 v59, v4
	v_mov_b32_e32 v60, v4
	v_mov_b32_e32 v61, v4
	v_mov_b32_e32 v62, v4
	v_mov_b32_e32 v63, v4
	v_mov_b32_e32 v64, v4
	v_mov_b32_e32 v65, v4
	v_mov_b32_e32 v66, v4
	v_mov_b32_e32 v67, v4
	v_mov_b32_e32 v68, v4
	v_mov_b32_e32 v69, v4
	v_mov_b32_e32 v70, v4
	v_mov_b32_e32 v71, v4
	v_mov_b32_e32 v72, v4
	v_mov_b32_e32 v73, v4
	v_mov_b32_e32 v74, v4
	v_mov_b32_e32 v75, v4
	v_mov_b32_e32 v76, v4
	v_mov_b32_e32 v77, v4
	v_mov_b32_e32 v78, v4
	v_mov_b32_e32 v79, v4
	v_mov_b32_e32 v80, v4
	v_mov_b32_e32 v81, v4
	v_mov_b32_e32 v82, v4
	v_mov_b32_e32 v83, v4
	v_mov_b32_e32 v84, v4
	v_mov_b32_e32 v85, v4
	v_mov_b32_e32 v86, v4
	v_mov_b32_e32 v87, v4
	v_mov_b32_e32 v88, v4
	v_mov_b32_e32 v89, v4
	v_mov_b32_e32 v90, v4
	v_mov_b32_e32 v91, v4
	v_mov_b32_e32 v92, v4
	v_mov_b32_e32 v93, v4
	v_mov_b32_e32 v94, v4
	v_mov_b32_e32 v95, v4
	v_mov_b32_e32 v96, v4
	v_mov_b32_e32 v97, v4
	v_mov_b32_e32 v98, v4
	v_mov_b32_e32 v99, v4
	v_mov_b32_e32 v116, v4
	v_mov_b32_e32 v117, v4
	v_mov_b32_e32 v118, v4
	v_mov_b32_e32 v119, v4
	v_mov_b32_e32 v120, v4
	v_mov_b32_e32 v121, v4
	v_mov_b32_e32 v122, v4
	v_mov_b32_e32 v123, v4
	v_mov_b32_e32 v124, v4
	v_mov_b32_e32 v125, v4
	v_mov_b32_e32 v126, v4
	v_mov_b32_e32 v127, v4
	v_mov_b32_e32 v128, v4
	v_mov_b32_e32 v129, v4
	v_mov_b32_e32 v130, v4
	v_mov_b32_e32 v131, v4
	v_mov_b32_e32 v100, v4
	v_mov_b32_e32 v101, v4
	v_mov_b32_e32 v102, v4
	v_mov_b32_e32 v103, v4
	v_mov_b32_e32 v104, v4
	v_mov_b32_e32 v105, v4
	v_mov_b32_e32 v106, v4
	v_mov_b32_e32 v107, v4
	v_mov_b32_e32 v108, v4
	v_mov_b32_e32 v109, v4
	v_mov_b32_e32 v110, v4
	v_mov_b32_e32 v111, v4
	v_mov_b32_e32 v112, v4
	v_mov_b32_e32 v113, v4
	v_mov_b32_e32 v114, v4
	v_mov_b32_e32 v115, v4
	.p2align 6
.LBB0_624:
	s_and_b32 s16, s14, 0x10000
	s_xor_b32 s17, s16, 0x10000
	v_xor_b32_e32 v217, s16, v215
	v_bitop3_b32 v218, v215, s16, 64 bitop3:0x96
	v_bitop3_b32 v220, v216, s16, 64 bitop3:0x96
	v_xor_b32_e32 v219, s17, v216
	v_xor_b32_e32 v221, s17, v215
	s_waitcnt lgkmcnt(3)
	v_mfma_f32_16x16x32_bf16 v[100:103], v[148:151], v[132:135], v[100:103]
	s_add_i32 s15, s14, 0x10000
	s_and_b32 s17, s15, 0x10000
	s_add_i32 s17, s0, s17
	v_lshl_add_u64 v[246:247], v[174:175], 0, s[12:13]
	s_add_i32 m0, s17, 0x800
	v_mfma_f32_16x16x32_bf16 v[104:107], v[148:151], v[136:139], v[104:107]
	v_mfma_f32_16x16x32_bf16 v[116:119], v[148:151], v[140:143], v[116:119]
	global_load_lds_dwordx4 v[246:247], off
	s_add_i32 m0, s17, 0x8800
	v_lshl_add_u64 v[248:249], v[176:177], 0, s[12:13]
	v_mfma_f32_16x16x32_bf16 v[120:123], v[148:151], v[144:147], v[120:123]
	ds_read_b128 v[148:151], v217 offset:8192
	s_waitcnt lgkmcnt(3)
	v_mfma_f32_16x16x32_bf16 v[108:111], v[152:155], v[132:135], v[108:111]
	ds_read_b128 v[222:225], v220
	v_mfma_f32_16x16x32_bf16 v[112:115], v[152:155], v[136:139], v[112:115]
	v_mfma_f32_16x16x32_bf16 v[124:127], v[152:155], v[140:143], v[124:127]
	global_load_lds_dwordx4 v[248:249], off
	s_add_i32 m0, s17, 0xc00
	v_lshl_add_u64 v[246:247], v[172:173], 0, s[12:13]
	v_mfma_f32_16x16x32_bf16 v[128:131], v[152:155], v[144:147], v[128:131]
	ds_read_b128 v[152:155], v217 offset:10240
	s_waitcnt lgkmcnt(4)
	v_mfma_f32_16x16x32_bf16 v[84:87], v[238:241], v[132:135], v[84:87]
	ds_read_b128 v[226:229], v220 offset:2048
	v_mfma_f32_16x16x32_bf16 v[88:91], v[238:241], v[136:139], v[88:91]
	v_mfma_f32_16x16x32_bf16 v[68:71], v[238:241], v[140:143], v[68:71]
	global_load_lds_dwordx4 v[246:247], off
	s_add_i32 m0, s17, 0x8c00
	v_lshl_add_u64 v[248:249], v[170:171], 0, s[12:13]
	v_mfma_f32_16x16x32_bf16 v[72:75], v[238:241], v[144:147], v[72:75]
	ds_read_b128 v[238:241], v217 offset:12288
	s_waitcnt lgkmcnt(5)
	v_mfma_f32_16x16x32_bf16 v[92:95], v[242:245], v[132:135], v[92:95]
	ds_read_b128 v[230:233], v220 offset:4096
	v_mfma_f32_16x16x32_bf16 v[96:99], v[242:245], v[136:139], v[96:99]
	v_mfma_f32_16x16x32_bf16 v[76:79], v[242:245], v[140:143], v[76:79]
	global_load_lds_dwordx4 v[248:249], off
	v_mfma_f32_16x16x32_bf16 v[80:83], v[242:245], v[144:147], v[80:83]
	ds_read_b128 v[242:245], v217 offset:14336
	s_waitcnt lgkmcnt(6)
	v_mfma_f32_16x16x32_bf16 v[52:55], v[148:151], v[132:135], v[52:55]
	ds_read_b128 v[234:237], v220 offset:6144
	v_mfma_f32_16x16x32_bf16 v[56:59], v[148:151], v[136:139], v[56:59]
	v_mfma_f32_16x16x32_bf16 v[36:39], v[148:151], v[140:143], v[36:39]
	v_mfma_f32_16x16x32_bf16 v[40:43], v[148:151], v[144:147], v[40:43]
	ds_read_b128 v[148:151], v218
	s_waitcnt lgkmcnt(6)
	v_mfma_f32_16x16x32_bf16 v[60:63], v[152:155], v[132:135], v[60:63]
	v_mfma_f32_16x16x32_bf16 v[64:67], v[152:155], v[136:139], v[64:67]
	v_mfma_f32_16x16x32_bf16 v[44:47], v[152:155], v[140:143], v[44:47]
	v_mfma_f32_16x16x32_bf16 v[48:51], v[152:155], v[144:147], v[48:51]
	ds_read_b128 v[152:155], v218 offset:2048
	s_waitcnt lgkmcnt(5)
	v_mfma_f32_16x16x32_bf16 v[20:23], v[238:241], v[132:135], v[20:23]
	v_mfma_f32_16x16x32_bf16 v[24:27], v[238:241], v[136:139], v[24:27]
	v_mfma_f32_16x16x32_bf16 v[4:7], v[238:241], v[140:143], v[4:7]
	v_mfma_f32_16x16x32_bf16 v[8:11], v[238:241], v[144:147], v[8:11]
	ds_read_b128 v[238:241], v218 offset:4096
	s_waitcnt lgkmcnt(4)
	v_mfma_f32_16x16x32_bf16 v[28:31], v[242:245], v[132:135], v[28:31]
	v_mfma_f32_16x16x32_bf16 v[32:35], v[242:245], v[136:139], v[32:35]
	v_mfma_f32_16x16x32_bf16 v[12:15], v[242:245], v[140:143], v[12:15]
	v_mfma_f32_16x16x32_bf16 v[16:19], v[242:245], v[144:147], v[16:19]
	ds_read_b128 v[242:245], v218 offset:6144
	s_waitcnt lgkmcnt(3)
	v_mfma_f32_16x16x32_bf16 v[100:103], v[148:151], v[222:225], v[100:103]
	v_mfma_f32_16x16x32_bf16 v[104:107], v[148:151], v[226:229], v[104:107]
	v_mfma_f32_16x16x32_bf16 v[116:119], v[148:151], v[230:233], v[116:119]
	v_mfma_f32_16x16x32_bf16 v[120:123], v[148:151], v[234:237], v[120:123]
	ds_read_b128 v[148:151], v218 offset:8192
	s_waitcnt lgkmcnt(3)
	v_mfma_f32_16x16x32_bf16 v[108:111], v[152:155], v[222:225], v[108:111]
	v_mfma_f32_16x16x32_bf16 v[112:115], v[152:155], v[226:229], v[112:115]
	v_mfma_f32_16x16x32_bf16 v[124:127], v[152:155], v[230:233], v[124:127]
	v_mfma_f32_16x16x32_bf16 v[128:131], v[152:155], v[234:237], v[128:131]
	ds_read_b128 v[152:155], v218 offset:10240
	s_waitcnt lgkmcnt(3)
	v_mfma_f32_16x16x32_bf16 v[84:87], v[238:241], v[222:225], v[84:87]
	v_mfma_f32_16x16x32_bf16 v[88:91], v[238:241], v[226:229], v[88:91]
	v_mfma_f32_16x16x32_bf16 v[68:71], v[238:241], v[230:233], v[68:71]
	v_mfma_f32_16x16x32_bf16 v[72:75], v[238:241], v[234:237], v[72:75]
	ds_read_b128 v[238:241], v218 offset:12288
	s_waitcnt lgkmcnt(3)
	v_mfma_f32_16x16x32_bf16 v[92:95], v[242:245], v[222:225], v[92:95]
	v_mfma_f32_16x16x32_bf16 v[96:99], v[242:245], v[226:229], v[96:99]
	v_mfma_f32_16x16x32_bf16 v[76:79], v[242:245], v[230:233], v[76:79]
	v_mfma_f32_16x16x32_bf16 v[80:83], v[242:245], v[234:237], v[80:83]
	ds_read_b128 v[242:245], v218 offset:14336
	s_waitcnt lgkmcnt(3)
	v_mfma_f32_16x16x32_bf16 v[52:55], v[148:151], v[222:225], v[52:55]
	v_mfma_f32_16x16x32_bf16 v[56:59], v[148:151], v[226:229], v[56:59]
	v_mfma_f32_16x16x32_bf16 v[36:39], v[148:151], v[230:233], v[36:39]
	v_mfma_f32_16x16x32_bf16 v[40:43], v[148:151], v[234:237], v[40:43]
	s_add_i32 s3, s3, 1
	s_min_i32 s38, s3, s1
	s_ashr_i32 s39, s38, 31
	s_lshl_b64 s[38:39], s[38:39], 7
	s_add_i32 s14, s0, s16
	v_lshl_add_u64 v[246:247], v[162:163], 0, s[38:39]
	s_mov_b32 m0, s14
	s_waitcnt vmcnt(0) lgkmcnt(0)
	s_barrier
	ds_read_b128 v[132:135], v219
	ds_read_b128 v[136:139], v219 offset:2048
	v_mfma_f32_16x16x32_bf16 v[60:63], v[152:155], v[222:225], v[60:63]
	ds_read_b128 v[140:143], v219 offset:4096
	ds_read_b128 v[144:147], v219 offset:6144
	v_mfma_f32_16x16x32_bf16 v[64:67], v[152:155], v[226:229], v[64:67]
	global_load_lds_dwordx4 v[246:247], off
	s_add_i32 m0, s14, 0x8000
	s_add_u32 s16, s38, s10
	v_lshl_add_u64 v[248:249], v[164:165], 0, s[38:39]
	s_addc_u32 s17, s39, s11
	ds_read_b128 v[148:151], v221
	v_mfma_f32_16x16x32_bf16 v[44:47], v[152:155], v[230:233], v[44:47]
	v_mfma_f32_16x16x32_bf16 v[48:51], v[152:155], v[234:237], v[48:51]
	global_load_lds_dwordx4 v[248:249], off
	s_add_i32 m0, s14, 0x400
	v_lshl_add_u64 v[246:247], v[166:167], 0, s[16:17]
	ds_read_b128 v[152:155], v221 offset:2048
	v_mfma_f32_16x16x32_bf16 v[20:23], v[238:241], v[222:225], v[20:23]
	v_mfma_f32_16x16x32_bf16 v[24:27], v[238:241], v[226:229], v[24:27]
	global_load_lds_dwordx4 v[246:247], off
	s_add_i32 m0, s14, 0x8400
	v_lshl_add_u64 v[248:249], v[168:169], 0, s[16:17]
	v_mfma_f32_16x16x32_bf16 v[4:7], v[238:241], v[230:233], v[4:7]
	v_mfma_f32_16x16x32_bf16 v[8:11], v[238:241], v[234:237], v[8:11]
	global_load_lds_dwordx4 v[248:249], off
	ds_read_b128 v[238:241], v221 offset:4096
	v_mfma_f32_16x16x32_bf16 v[28:31], v[242:245], v[222:225], v[28:31]
	v_mfma_f32_16x16x32_bf16 v[32:35], v[242:245], v[226:229], v[32:35]
	v_mfma_f32_16x16x32_bf16 v[12:15], v[242:245], v[230:233], v[12:15]
	v_mfma_f32_16x16x32_bf16 v[16:19], v[242:245], v[234:237], v[16:19]
	ds_read_b128 v[242:245], v221 offset:6144
	s_add_u32 s12, s12, 0x80
	s_addc_u32 s13, s13, 0
	s_cmp_eq_u32 s5, s3
	s_mov_b32 s14, s15
	s_cbranch_scc0 .LBB0_624
	s_branch .LBB0_626

.LBB0_1223:
	s_add_i32 s0, s86, 1
	s_cmp_ge_i32 s0, s87
	v_readlane_b32 s4, v250, 23
	s_cselect_b64 s[2:3], -1, 0
	v_readlane_b32 s5, v250, 24
	s_or_b64 s[2:3], s[2:3], s[4:5]
	s_and_b64 vcc, exec, s[2:3]
	s_cbranch_vccnz .LBB0_1249
	s_waitcnt lgkmcnt(0)
	v_readlane_b32 s12, v251, 56
	s_cmp_lg_u32 s86, 99
	s_mov_b64 s[2:3], -1
	v_readlane_b32 s20, v250, 0
	v_readlane_b32 s21, v250, 1
	v_readlane_b32 s13, v251, 57
	v_readlane_b32 s14, v251, 58
	v_readlane_b32 s15, v251, 59
	v_readlane_b32 s16, v251, 60
	v_readlane_b32 s17, v251, 61
	v_readlane_b32 s18, v251, 62
	v_readlane_b32 s19, v251, 63
	v_readlane_b32 s22, v250, 2
	v_readlane_b32 s23, v250, 3
	v_readlane_b32 s24, v250, 4
	v_readlane_b32 s25, v250, 5
	v_readlane_b32 s26, v250, 6
	v_readlane_b32 s27, v250, 7
	v_readlane_b32 s28, v250, 8
	s_cbranch_scc0 .LBB0_1239
	s_waitcnt vmcnt(0) lgkmcnt(0)
	v_add_u32_e32 v0, 1, v212
	s_barrier
	s_mov_b64 s[2:3], exec
	v_readlane_b32 s4, v251, 25
	v_readlane_b32 s5, v251, 26
	s_and_b64 s[4:5], s[2:3], s[4:5]
	s_xor_b64 s[2:3], s[4:5], s[2:3]
	s_mov_b64 exec, s[4:5]
	v_add_u32_e32 v0, 1, v212
	s_andn2_saveexec_b64 s[2:3], s[2:3]
	s_cbranch_execz .LBB0_1238
	s_mov_b64 s[6:7], exec
	buffer_wbl2 sc1
	s_waitcnt vmcnt(0)
	s_waitcnt vmcnt(0)
	v_mbcnt_lo_u32_b32 v1, s6, 0
	v_mbcnt_hi_u32_b32 v1, s7, v1
	v_cmp_eq_u32_e32 vcc, 0, v1
	s_and_saveexec_b64 s[8:9], vcc
	s_cbranch_execz .LBB0_1230
	s_bcnt1_i32_b64 s1, s[6:7]
	v_mov_b32_e32 v3, s1
	global_atomic_add v3, v2, v3, s[20:21] sc0
